# v15 + kernel entry: all three kernarg scalar loads issued together before the first wait (one cold round trip instead of two)
# speedup vs baseline: 1.0042x; 1.0016x over previous
; #define LAS __attribute__((address_space(3)))
; __device__ __forceinline__ unsigned xb_add(unsigned* p, unsigned v) { return __hip_atomic_fetch_add(p, v, __ATOMIC_RELAXED, __HIP_MEMORY_SCOPE_AGENT); }
; __device__ __forceinline__ unsigned xb_xcc_id() { return (unsigned)__builtin_amdgcn_s_getreg((3 << 11) | 20) & 0xFu; }
; __device__ __forceinline__ XcdBarrier xcd_barrier_post(unsigned* bar, volatile LAS unsigned* st) {
;     XcdBarrier b; b.bar = bar; b.x = xb_xcc_id(); b.st = st;
;     if (threadIdx.x == 0) (void)xb_add(&bar[XB_XCNT(b.x)], 1u);
;     return b;
; __global__ __launch_bounds__(512, 2) void hymba_fwd(Params p) {
;     ...
;     const int bid = blockIdx.x;
;     unsigned char* ws = p.ws;
;     ...
;     constexpr int lo = 0, hi = NPH;
;     ...
;     const int lo = p.ph_lo, hi = p.ph_hi;
;     ...
;     if (threadIdx.x < 4) ((LAS unsigned*)(lds + LDS_CTL))[threadIdx.x] = 0u;
;     __syncthreads();
;     XcdBarrier xbar = xcd_barrier_post((unsigned*)(ws + WS_BAR), (volatile LAS unsigned*)(lds + LDS_CTL));
_Z9hymba_fwd6Params:
	s_load_dwordx2 s[4:5], s[0:1], 0x80
	s_load_dwordx16 s[76:91], s[0:1], 0x0
	s_load_dwordx16 s[60:75], s[0:1], 0x40
	v_cmp_gt_u32_e32 vcc, 4, v0
	v_lshl_add_u32 v27, v0, 2, 0
	s_waitcnt lgkmcnt(0)
	v_writelane_b32 v255, s4, 0
	s_nop 1
	v_writelane_b32 v255, s5, 1
	s_and_saveexec_b64 s[4:5], vcc
	v_add_u32_e32 v1, 0x22000, v27
	v_mov_b32_e32 v2, 0
	ds_write_b32 v1, v2
	s_or_b64 exec, exec, s[4:5]
	v_readlane_b32 s0, v255, 0
	v_readlane_b32 s1, v255, 1
	s_add_u32 s0, s0, 0xbd00000
	s_addc_u32 s1, s1, 0
	v_writelane_b32 v255, s0, 2
	s_waitcnt lgkmcnt(0)
	s_barrier
	v_writelane_b32 v255, s1, 3
	s_getreg_b32 s0, hwreg(HW_REG_XCC_ID, 0, 4)
	s_and_b32 s46, s0, 15
	v_cmp_eq_u32_e64 s[92:93], 0, v0
	s_and_saveexec_b64 s[4:5], s[92:93]
	s_cbranch_execz .LBB0_5
	s_mov_b64 s[6:7], exec
	v_mbcnt_lo_u32_b32 v1, s6, 0
	v_mbcnt_hi_u32_b32 v1, s7, v1
	v_cmp_eq_u32_e32 vcc, 0, v1
	s_and_b64 s[0:1], exec, vcc
	s_mov_b64 exec, s[0:1]
	s_cbranch_execz .LBB0_5
	s_lshl_b32 s0, s46, 8
	s_bcnt1_i32_b64 s1, s[6:7]
	v_mov_b32_e32 v1, s0
	v_mov_b32_e32 v2, s1
	v_readlane_b32 s0, v255, 2
	v_readlane_b32 s1, v255, 3
	s_nop 4
	global_atomic_add v1, v2, s[0:1] offset:1024
